# attention P.V blocks: counted lgkmcnt waits per MFMA instead of a full drain per 4-MFMA group
# speedup vs baseline: 1.0055x; 1.0055x over previous
.LBB0_528:
	s_cmp_eq_u32 s96, 2
	s_cbranch_scc1 .LBB0_531
	s_add_i32 s8, s8, -3
	s_cmp_gt_i32 s8, -1
	s_cselect_b64 s[8:9], -1, 0
	s_sub_i32 s10, s95, 64
	s_cmp_gt_i32 s10, s68
	s_cselect_b64 s[10:11], -1, 0
	s_and_b64 s[8:9], s[8:9], s[10:11]
	s_and_b64 vcc, exec, s[8:9]
	s_cbranch_vccnz .LBB0_531
	v_lshl_add_u32 v0, s6, 14, v202
	ds_read_b64_tr_b16 v[2:3], v0 offset:0
	ds_read_b64_tr_b16 v[4:5], v0 offset:0x800
	ds_read_b64_tr_b16 v[6:7], v0 offset:0x1000
	ds_read_b64_tr_b16 v[8:9], v0 offset:0x1800
	ds_read_b64_tr_b16 v[10:11], v0 offset:0x2000
	ds_read_b64_tr_b16 v[12:13], v0 offset:0x2800
	ds_read_b64_tr_b16 v[210:211], v0 offset:0x3000
	ds_read_b64_tr_b16 v[212:213], v0 offset:0x3800
	s_waitcnt lgkmcnt(6)
	s_nop 0
	v_mfma_f32_32x32x16_bf16 v[64:79], v[2:5], v[156:159], v[64:79]
	ds_read_b64_tr_b16 v[2:3], v0 offset:0x200
	ds_read_b64_tr_b16 v[4:5], v0 offset:0xa00
	s_waitcnt lgkmcnt(6)
	v_mfma_f32_32x32x16_bf16 v[64:79], v[6:9], v[152:155], v[64:79]
	ds_read_b64_tr_b16 v[6:7], v0 offset:0x1200
	ds_read_b64_tr_b16 v[8:9], v0 offset:0x1a00
	s_waitcnt lgkmcnt(6)
	v_mfma_f32_32x32x16_bf16 v[64:79], v[10:13], v[148:151], v[64:79]
	ds_read_b64_tr_b16 v[10:11], v0 offset:0x2200
	ds_read_b64_tr_b16 v[12:13], v0 offset:0x2a00
	s_waitcnt lgkmcnt(6)
	v_mfma_f32_32x32x16_bf16 v[64:79], v[210:213], v[144:147], v[64:79]
	ds_read_b64_tr_b16 v[210:211], v0 offset:0x3200
	ds_read_b64_tr_b16 v[212:213], v0 offset:0x3a00
	s_waitcnt lgkmcnt(6)
	v_mfma_f32_32x32x16_bf16 v[48:63], v[2:5], v[156:159], v[48:63]
	ds_read_b64_tr_b16 v[2:3], v0 offset:0x400
	ds_read_b64_tr_b16 v[4:5], v0 offset:0xc00
	s_waitcnt lgkmcnt(6)
	v_mfma_f32_32x32x16_bf16 v[48:63], v[6:9], v[152:155], v[48:63]
	ds_read_b64_tr_b16 v[6:7], v0 offset:0x1400
	ds_read_b64_tr_b16 v[8:9], v0 offset:0x1c00
	s_waitcnt lgkmcnt(6)
	v_mfma_f32_32x32x16_bf16 v[48:63], v[10:13], v[148:151], v[48:63]
	ds_read_b64_tr_b16 v[10:11], v0 offset:0x2400
	ds_read_b64_tr_b16 v[12:13], v0 offset:0x2c00
	s_waitcnt lgkmcnt(6)
	v_mfma_f32_32x32x16_bf16 v[48:63], v[210:213], v[144:147], v[48:63]
	ds_read_b64_tr_b16 v[210:211], v0 offset:0x3400
	ds_read_b64_tr_b16 v[212:213], v0 offset:0x3c00
	s_waitcnt lgkmcnt(6)
	v_mfma_f32_32x32x16_bf16 v[32:47], v[2:5], v[156:159], v[32:47]
	ds_read_b64_tr_b16 v[2:3], v0 offset:0x600
	ds_read_b64_tr_b16 v[4:5], v0 offset:0xe00
	s_waitcnt lgkmcnt(6)
	v_mfma_f32_32x32x16_bf16 v[32:47], v[6:9], v[152:155], v[32:47]
	ds_read_b64_tr_b16 v[6:7], v0 offset:0x1600
	ds_read_b64_tr_b16 v[8:9], v0 offset:0x1e00
	s_waitcnt lgkmcnt(6)
	v_mfma_f32_32x32x16_bf16 v[32:47], v[10:13], v[148:151], v[32:47]
	ds_read_b64_tr_b16 v[10:11], v0 offset:0x2600
	ds_read_b64_tr_b16 v[12:13], v0 offset:0x2e00
	s_waitcnt lgkmcnt(6)
	v_mfma_f32_32x32x16_bf16 v[32:47], v[210:213], v[144:147], v[32:47]
	ds_read_b64_tr_b16 v[210:211], v0 offset:0x3600
	ds_read_b64_tr_b16 v[212:213], v0 offset:0x3e00
	s_waitcnt lgkmcnt(6)
	v_mfma_f32_32x32x16_bf16 v[16:31], v[2:5], v[156:159], v[16:31]
	s_waitcnt lgkmcnt(4)
	v_mfma_f32_32x32x16_bf16 v[16:31], v[6:9], v[152:155], v[16:31]
	s_waitcnt lgkmcnt(2)
	v_mfma_f32_32x32x16_bf16 v[16:31], v[10:13], v[148:151], v[16:31]
	s_waitcnt lgkmcnt(0)
	v_mfma_f32_32x32x16_bf16 v[16:31], v[210:213], v[144:147], v[16:31]

.LBB0_575:
	s_cmp_eq_u32 s0, 0
	s_cbranch_scc1 .LBB0_578
	s_add_i32 s9, s7, -1
	s_cmp_gt_i32 s9, -1
	s_cselect_b64 s[10:11], -1, 0
	s_add_i32 s9, s8, 0xffffff40
	s_cmp_gt_i32 s9, s95
	s_cselect_b64 s[12:13], -1, 0
	s_and_b64 s[10:11], s[10:11], s[12:13]
	s_and_b64 vcc, exec, s[10:11]
	s_cbranch_vccnz .LBB0_578
	v_lshl_add_u32 v14, s6, 14, v202
	ds_read_b64_tr_b16 v[2:3], v14 offset:0
	ds_read_b64_tr_b16 v[4:5], v14 offset:0x800
	ds_read_b64_tr_b16 v[6:7], v14 offset:0x1000
	ds_read_b64_tr_b16 v[8:9], v14 offset:0x1800
	ds_read_b64_tr_b16 v[10:11], v14 offset:0x2000
	ds_read_b64_tr_b16 v[12:13], v14 offset:0x2800
	ds_read_b64_tr_b16 v[174:175], v14 offset:0x3000
	ds_read_b64_tr_b16 v[176:177], v14 offset:0x3800
	s_waitcnt lgkmcnt(6)
	s_nop 0
	v_mfma_f32_32x32x16_bf16 v[64:79], v[2:5], v[140:143], v[64:79]
	ds_read_b64_tr_b16 v[2:3], v14 offset:0x200
	ds_read_b64_tr_b16 v[4:5], v14 offset:0xa00
	s_waitcnt lgkmcnt(6)
	v_mfma_f32_32x32x16_bf16 v[64:79], v[6:9], v[136:139], v[64:79]
	ds_read_b64_tr_b16 v[6:7], v14 offset:0x1200
	ds_read_b64_tr_b16 v[8:9], v14 offset:0x1a00
	s_waitcnt lgkmcnt(6)
	v_mfma_f32_32x32x16_bf16 v[64:79], v[10:13], v[132:135], v[64:79]
	ds_read_b64_tr_b16 v[10:11], v14 offset:0x2200
	ds_read_b64_tr_b16 v[12:13], v14 offset:0x2a00
	s_waitcnt lgkmcnt(6)
	v_mfma_f32_32x32x16_bf16 v[64:79], v[174:177], v[128:131], v[64:79]
	ds_read_b64_tr_b16 v[174:175], v14 offset:0x3200
	ds_read_b64_tr_b16 v[176:177], v14 offset:0x3a00
	s_waitcnt lgkmcnt(6)
	v_mfma_f32_32x32x16_bf16 v[48:63], v[2:5], v[140:143], v[48:63]
	ds_read_b64_tr_b16 v[2:3], v14 offset:0x400
	ds_read_b64_tr_b16 v[4:5], v14 offset:0xc00
	s_waitcnt lgkmcnt(6)
	v_mfma_f32_32x32x16_bf16 v[48:63], v[6:9], v[136:139], v[48:63]
	ds_read_b64_tr_b16 v[6:7], v14 offset:0x1400
	ds_read_b64_tr_b16 v[8:9], v14 offset:0x1c00
	s_waitcnt lgkmcnt(6)
	v_mfma_f32_32x32x16_bf16 v[48:63], v[10:13], v[132:135], v[48:63]
	ds_read_b64_tr_b16 v[10:11], v14 offset:0x2400
	ds_read_b64_tr_b16 v[12:13], v14 offset:0x2c00
	s_waitcnt lgkmcnt(6)
	v_mfma_f32_32x32x16_bf16 v[48:63], v[174:177], v[128:131], v[48:63]
	ds_read_b64_tr_b16 v[174:175], v14 offset:0x3400
	ds_read_b64_tr_b16 v[176:177], v14 offset:0x3c00
	s_waitcnt lgkmcnt(6)
	v_mfma_f32_32x32x16_bf16 v[32:47], v[2:5], v[140:143], v[32:47]
	ds_read_b64_tr_b16 v[2:3], v14 offset:0x600
	ds_read_b64_tr_b16 v[4:5], v14 offset:0xe00
	s_waitcnt lgkmcnt(6)
	v_mfma_f32_32x32x16_bf16 v[32:47], v[6:9], v[136:139], v[32:47]
	ds_read_b64_tr_b16 v[6:7], v14 offset:0x1600
	ds_read_b64_tr_b16 v[8:9], v14 offset:0x1e00
	s_waitcnt lgkmcnt(6)
	v_mfma_f32_32x32x16_bf16 v[32:47], v[10:13], v[132:135], v[32:47]
	ds_read_b64_tr_b16 v[10:11], v14 offset:0x2600
	ds_read_b64_tr_b16 v[12:13], v14 offset:0x2e00
	s_waitcnt lgkmcnt(6)
	v_mfma_f32_32x32x16_bf16 v[32:47], v[174:177], v[128:131], v[32:47]
	ds_read_b64_tr_b16 v[174:175], v14 offset:0x3600
	ds_read_b64_tr_b16 v[176:177], v14 offset:0x3e00
	s_waitcnt lgkmcnt(6)
	v_mfma_f32_32x32x16_bf16 v[16:31], v[2:5], v[140:143], v[16:31]
	s_waitcnt lgkmcnt(4)
	v_mfma_f32_32x32x16_bf16 v[16:31], v[6:9], v[136:139], v[16:31]
	s_waitcnt lgkmcnt(2)
	v_mfma_f32_32x32x16_bf16 v[16:31], v[10:13], v[132:135], v[16:31]
	s_waitcnt lgkmcnt(0)
	v_mfma_f32_32x32x16_bf16 v[16:31], v[174:177], v[128:131], v[16:31]
